# P3: V tile unpadded with XOR-swizzled 32B chunks so transposed LDS reads are bank-conflict-free
# speedup vs baseline: 1.0179x; 1.0020x over previous
.LBB0_343:
	s_load_dwordx4 s[24:27], s[6:7], 0x60
	s_load_dwordx4 s[8:11], s[6:7], 0x40
	v_and_b32_e32 v123, 15, v158
	v_and_b32_e32 v0, 48, v158
	s_movk_i32 s12, 0x110
	s_waitcnt lgkmcnt(0)
	s_add_u32 s33, s26, 0x900000
	s_addc_u32 s50, s27, 0
	s_add_u32 s51, s26, 0x2000000
	s_addc_u32 s52, s27, 0
	s_add_u32 s53, s26, 0xa000000
	v_bfe_u32 v2, v158, 4, 2
	s_addc_u32 s54, s27, 0
	v_mad_u32_u24 v3, v123, s12, v0
	v_bfe_u32 v0, v158, 2, 2
	s_add_u32 s55, s26, 0x12000000
	v_lshlrev_b32_e32 v120, 3, v158
	s_waitcnt vmcnt(0)
	v_lshl_or_b32 v5, v2, 3, v0
	v_lshlrev_b32_e32 v124, 2, v2
	v_lshlrev_b32_e32 v2, 7, v123
	s_addc_u32 s56, s27, 0
	v_and_b32_e32 v4, 0x3f8, v120
	v_mov_b32_e32 v121, 0
	v_sub_u32_e32 v2, v3, v2
	s_add_i32 s57, 0, 0x15800
	s_add_i32 s14, 0, 0x1a000
	s_add_i32 s58, 0, 0x17c00
	s_mov_b32 s35, 0
	v_lshlrev_b32_e32 v125, 4, v158
	v_add_u32_e32 v155, 0, v3
	v_add_u32_e32 v156, s57, v2
	v_add_u32_e32 v157, s14, v3
	v_add_u32_e32 v159, s58, v2
	v_lshlrev_b32_e32 v2, 2, v4
	v_mov_b32_e32 v3, v121
	v_and_b32_e32 v1, 63, v158
	s_mov_b32 s3, s35
	v_and_b32_e32 v6, 24, v120
	v_and_b32_e32 v9, 0xf0, v125
	s_add_i32 s13, 0, 0xf000
	v_lshl_add_u64 v[126:127], s[8:9], 0, v[2:3]
	s_mov_b64 s[8:9], 0x1000
	s_lshl_b64 s[6:7], s[2:3], 12
	v_lshlrev_b32_e32 v0, 2, v1
	v_lshlrev_b32_e32 v154, 4, v1
	v_mad_u32_u24 v1, v5, s12, v6
	v_add_u32_e32 v6, s13, v9
	s_add_i32 s13, 0, 0x13400
	v_lshl_add_u64 v[128:129], v[126:127], 0, s[8:9]
	s_mov_b64 s[8:9], 0x2000
	v_lshl_add_u64 v[132:133], s[10:11], 0, v[2:3]
	v_lshlrev_b32_e32 v2, 1, v4
	v_lshl_add_u64 v[130:131], v[126:127], 0, s[8:9]
	v_lshl_add_u64 v[2:3], s[26:27], 0, v[2:3]
	s_mov_b64 s[8:9], 0x16000000
	s_add_u32 s6, s26, s6
	v_lshl_add_u64 v[134:135], v[2:3], 0, s[8:9]
	s_mov_b64 s[8:9], 0x1a000000
	s_addc_u32 s7, s27, s7
	v_lshlrev_b32_e32 v5, 7, v5
	v_lshl_add_u64 v[136:137], v[2:3], 0, s[8:9]
	v_lshl_add_u64 v[2:3], s[6:7], 0, v[120:121]
	s_mov_b64 s[6:7], 0x1e000000
	v_lshrrev_b32_e32 v122, 7, v158
	v_sub_u32_e32 v5, v1, v5
	v_add_u32_e32 v160, 0, v1
	v_mov_b32_e32 v1, s14
	v_lshl_add_u64 v[138:139], v[2:3], 0, s[6:7]
	s_ashr_i32 s31, s30, 31
	v_and_b32_e32 v2, 0x7f, v158
	v_mad_u32_u24 v163, v123, s12, v1
	s_lshl_b64 s[6:7], s[30:31], 19
	v_lshlrev_b32_e32 v1, 12, v122
	v_lshlrev_b32_e32 v2, 4, v2
	v_lshrrev_b32_e32 v7, 4, v158
	v_lshrrev_b32_e32 v10, 3, v158
	s_movk_i32 s3, 0x90
	v_mov_b32_e32 v13, s13
	v_or3_b32 v2, s6, v1, v2
	v_mov_b32_e32 v3, s7
	v_mul_u32_u24_e32 v8, 0x110, v7
	v_mad_u32_u24 v7, v7, s12, 0
	v_mad_u32_u24 v11, v10, s3, 0
	v_and_b32_e32 v12, 0x70, v125
	v_mad_u32_u24 v10, v10, s3, v13
	v_lshl_add_u64 v[2:3], s[26:27], 0, v[2:3]
	s_mov_b64 s[6:7], 0xa000800
	s_ashr_i32 s29, s28, 31
	v_add_u32_e32 v161, 0, v5
	v_add_u32_e32 v162, s13, v5
	v_or_b32_e32 v164, 16, v123
	v_lshl_add_u64 v[140:141], v[2:3], 0, s[6:7]
	s_lshl_b64 s[26:27], s[28:29], 19
	v_lshl_or_b32 v165, s30, 7, v122
	s_lshl_b32 s29, s28, 7
	s_brev_b32 s59, 64
	v_lshlrev_b32_e32 v120, 1, v120
	s_movk_i32 s60, 0x2000
	v_lshlrev_b32_e32 v142, 2, v0
	v_add_u32_e32 v166, v6, v8
	v_add_u32_e32 v167, v10, v12
	s_add_i32 s61, 0, 0x1e800
	s_movk_i32 s62, 0xfff
	s_mov_b64 s[36:37], 0x4000
	v_add_u32_e32 v168, v7, v9
	v_add_u32_e32 v169, v11, v12
	v_lshrrev_b32_e32 v240, 3, v158
	v_and_b32_e32 v241, 7, v158
	v_lshrrev_b32_e32 v242, 1, v241
	v_and_b32_e32 v241, 1, v241
	v_bfe_u32 v243, v240, 1, 1
	v_bfe_u32 v244, v240, 3, 1
	v_lshl_or_b32 v243, v244, 1, v243
	v_xor_b32_e32 v242, v242, v243
	v_lshlrev_b32_e32 v240, 7, v240
	v_lshl_add_u32 v240, v242, 5, v240
	v_lshl_add_u32 v169, v241, 4, v240
	v_add_u32_e32 v167, 0x13400, v169

.LBB0_349:
	s_lshr_b32 s34, s16, 6
	s_and_b64 s[18:19], exec, s[38:39]
	s_cselect_b32 s7, 0, 0x4000000
	s_add_u32 s7, s24, s7
	s_addc_u32 s9, s25, 0
	s_ashr_i32 s11, s10, 31
	s_lshl_b64 s[18:19], s[10:11], 20
	s_add_u32 s43, s7, s18
	s_addc_u32 s63, s9, s19
	s_and_b64 s[44:45], exec, s[38:39]
	s_cselect_b32 s7, s59, 0x6000000
	s_add_u32 s7, s24, s7
	s_addc_u32 s9, s25, 0
	s_add_u32 s64, s7, s18
	s_addc_u32 s65, s9, s19
	s_lshl_b64 s[14:15], s[14:15], 1
	s_add_u32 s46, s51, s14
	s_addc_u32 s47, s52, s15
	s_lshl_b32 s7, s10, 7
	s_lshl_b32 s9, s17, 6
	s_or_b32 s10, s7, s9
	s_ashr_i32 s11, s10, 31
	s_lshl_b64 s[10:11], s[10:11], 10
	s_ashr_i32 s31, s30, 31
	s_add_u32 s48, s33, s10
	s_addc_u32 s49, s50, s11
	s_lshr_b32 s18, s16, 7
	s_lshl_b64 s[10:11], s[30:31], 7
	s_bfe_u32 s31, s16, 0x20006
	s_and_b32 s66, s18, 0x1fffffe
	s_lshl_b32 s7, s12, 13
	s_lshl_b32 s9, s12, 14
	s_add_u32 s14, s43, s9
	s_addc_u32 s15, s63, 0
	v_lshl_add_u64 v[0:1], s[14:15], 0, v[120:121]
	s_add_u32 s16, s64, s9
	v_add_co_u32_e32 v0, vcc, s60, v0
	s_addc_u32 s17, s65, 0
	s_nop 0
	v_addc_co_u32_e32 v1, vcc, 0, v1, vcc
	v_lshl_add_u64 v[2:3], s[16:17], 0, v[120:121]
	v_add_co_u32_e32 v2, vcc, s60, v2
	global_load_dwordx4 v[56:59], v120, s[14:15]
	global_load_dwordx4 v[60:63], v120, s[16:17]
	v_addc_co_u32_e32 v3, vcc, 0, v3, vcc
	global_load_dwordx4 v[64:67], v[0:1], off
	global_load_dwordx4 v[68:71], v[2:3], off
	s_add_u32 s14, s46, s7
	s_addc_u32 s15, s47, 0
	global_load_dwordx4 v[72:75], v120, s[14:15]
	s_lshl_b32 s7, s12, 10
	s_add_u32 s12, s48, s7
	s_addc_u32 s13, s49, 0
	global_load_dwordx4 v[76:79], v142, s[12:13]
	global_load_dwordx4 v[0:3], v[126:127], off
	global_load_dwordx4 v[4:7], v[126:127], off offset:16
	global_load_dwordx4 v[8:11], v[128:129], off
	global_load_dwordx4 v[12:15], v[128:129], off offset:16
	global_load_dwordx4 v[16:19], v[130:131], off
	global_load_dwordx4 v[20:23], v[130:131], off offset:16
	global_load_dwordx4 v[24:27], v[132:133], off
	global_load_dwordx4 v[28:31], v[132:133], off offset:16
	s_waitcnt vmcnt(34)
	v_add_u32_e32 v32, 0, v154
	v_or_b32_e32 v144, s10, v122
	v_mov_b32_e32 v33, v121
	s_waitcnt vmcnt(20)
	v_add_u32_e32 v82, 0x1e400, v32
	v_and_b32_e32 v32, 0xf87, v144
	v_cmp_ne_u64_e32 vcc, 0, v[32:33]
	s_lshl_b32 s7, s8, 13
	s_lshl_b32 s9, s8, 14
	v_cndmask_b32_e64 v32, 0, 1, vcc
	s_add_u32 s10, s43, s9
	v_mov_b32_e32 v145, s11
	v_mov_b32_e32 v34, s11
	v_sub_co_u32_e32 v80, vcc, v144, v32
	s_addc_u32 s11, s63, 0
	s_nop 0
	v_subbrev_co_u32_e32 v81, vcc, 0, v34, vcc
	v_lshl_add_u64 v[36:37], s[10:11], 0, v[120:121]
	global_load_dwordx4 v[32:35], v120, s[10:11]
	s_add_u32 s10, s64, s9
	v_add_co_u32_e32 v36, vcc, s60, v36
	s_addc_u32 s11, s65, 0
	s_nop 0
	v_addc_co_u32_e32 v37, vcc, 0, v37, vcc
	v_lshl_add_u64 v[38:39], s[10:11], 0, v[120:121]
	s_add_u32 s12, s46, s7
	v_add_co_u32_e32 v40, vcc, s60, v38
	s_addc_u32 s13, s47, 0
	s_lshl_b32 s7, s8, 10
	v_addc_co_u32_e32 v41, vcc, 0, v39, vcc
	s_add_u32 s8, s48, s7
	global_load_dwordx4 v[36:39], v[36:37], off
	s_nop 0
	global_load_dwordx4 v[44:47], v[40:41], off
	s_nop 0
	global_load_dwordx4 v[40:43], v120, s[10:11]
	global_load_dwordx4 v[48:51], v120, s[12:13]
	s_addc_u32 s9, s49, 0
	s_lshl_b32 s7, s6, 13
	s_lshl_b32 s10, s6, 14
	global_load_dwordx4 v[52:55], v142, s[8:9]
	s_add_u32 s8, s43, s10
	s_addc_u32 s9, s63, 0
	s_add_u32 s10, s64, s10
	s_addc_u32 s11, s65, 0
	s_mul_i32 s67, s31, 0x1100
	v_add_u32_e32 v170, s67, v155
	v_lshl_or_b32 v173, s66, 4, v123
	v_mul_lo_u32 v174, v173, s3
	s_mov_b32 s44, 0
	s_mov_b32 s45, s44
	v_mov_b32_e32 v143, v121
	v_lshl_add_u32 v178, s34, 5, v160
	v_add_u32_e32 v181, 0xf000, v178
	v_add_u32_e32 v183, s67, v157
	s_waitcnt vmcnt(19)
	ds_write_b128 v168, v[56:59]
	s_waitcnt vmcnt(17)
	ds_write_b128 v168, v[64:67] offset:8704
	ds_write_b128 v168, v[60:63] offset:17408
	s_waitcnt vmcnt(16)
	ds_write_b128 v168, v[68:71] offset:26112
	s_waitcnt vmcnt(15)
	ds_write_b128 v169, v[72:75] offset:34816
	s_waitcnt vmcnt(14)
	ds_write_b128 v82, v[76:79]
	v_lshlrev_b64 v[56:57], 11, v[80:81]
	v_lshlrev_b64 v[64:65], 11, v[144:145]
	v_lshl_add_u64 v[72:73], s[8:9], 0, v[120:121]
	v_lshl_add_u64 v[56:57], v[134:135], 0, v[56:57]
	v_lshl_add_u64 v[66:67], v[134:135], 0, v[64:65]
	v_lshl_add_u64 v[68:69], v[136:137], 0, v[64:65]
	v_add_co_u32_e32 v80, vcc, s60, v72
	global_load_dwordx4 v[56:59], v[56:57], off
	s_nop 0
	global_load_dwordx4 v[60:63], v[66:67], off
	s_nop 0
	global_load_dwordx4 v[64:67], v[66:67], off offset:2048
	s_nop 0
	global_load_dwordx4 v[68:71], v[68:69], off
	v_addc_co_u32_e32 v81, vcc, 0, v73, vcc
	global_load_dwordx4 v[72:75], v120, s[8:9]
	global_load_dwordx4 v[76:79], v120, s[10:11]
	s_add_u32 s8, s46, s7
	v_lshl_add_u64 v[82:83], s[10:11], 0, v[120:121]
	s_addc_u32 s9, s47, 0
	s_lshl_b32 s6, s6, 10
	v_add_co_u32_e32 v84, vcc, s60, v82
	s_add_u32 s6, s48, s6
	s_nop 0
	v_addc_co_u32_e32 v85, vcc, 0, v83, vcc
	s_addc_u32 s7, s49, 0
	global_load_dwordx4 v[80:83], v[80:81], off
	s_nop 0
	global_load_dwordx4 v[84:87], v[84:85], off
	s_lshl_b32 s12, s18, 4
	global_load_dwordx4 v[88:91], v120, s[8:9]
	global_load_dwordx4 v[92:95], v142, s[6:7]
	s_waitcnt lgkmcnt(0)
	s_barrier
	ds_read_b128 v[96:99], v170 offset:17408
	s_mul_i32 s6, s66, 0x1100
	v_add_u32_e32 v171, s6, v155
	ds_read_b128 v[100:103], v171
	s_or_b32 s68, s12, 16
	ds_read_b128 v[104:107], v170 offset:17472
	ds_read_b128 v[108:111], v171 offset:64
	s_mul_i32 s6, s68, 0x110
	s_waitcnt lgkmcnt(2)
	v_mfma_f32_16x16x32_bf16 v[100:103], v[96:99], v[100:103], 0
	v_add_u32_e32 v172, s6, v155
	ds_read_b128 v[112:115], v172
	ds_read_b128 v[116:119], v172 offset:64
	v_or_b32_e32 v179, s68, v123
	s_waitcnt lgkmcnt(2)
	v_mfma_f32_16x16x32_bf16 v[100:103], v[104:107], v[108:111], v[100:103]
	ds_read_b128 v[108:111], v170 offset:17536
	v_mov_b32_e32 v184, v165
	v_mov_b64_e32 v[152:153], v[140:141]
	s_waitcnt lgkmcnt(2)
	v_mfma_f32_16x16x32_bf16 v[96:99], v[96:99], v[112:115], 0
	s_waitcnt lgkmcnt(1)
	v_mfma_f32_16x16x32_bf16 v[96:99], v[104:107], v[116:119], v[96:99]
	ds_read_b128 v[104:107], v171 offset:128
	ds_read_b128 v[112:115], v170 offset:17600
	ds_read_b128 v[116:119], v171 offset:192
	s_waitcnt lgkmcnt(2)
	v_mfma_f32_16x16x32_bf16 v[100:103], v[108:111], v[104:107], v[100:103]
	ds_read_b128 v[104:107], v172 offset:128
	ds_read_b128 v[146:149], v172 offset:192
	s_waitcnt lgkmcnt(1)
	v_mfma_f32_16x16x32_bf16 v[96:99], v[108:111], v[104:107], v[96:99]
	v_lshl_or_b32 v104, s31, 4, v124
	v_or_b32_e32 v107, 2, v104
	v_or_b32_e32 v108, 3, v104
	v_mfma_f32_16x16x32_bf16 v[100:103], v[112:115], v[116:119], v[100:103]
	v_cmp_gt_u32_e32 vcc, v104, v173
	v_cmp_ge_u32_e64 s[6:7], v104, v173
	v_cmp_gt_u32_e64 s[8:9], v107, v173
	v_cmp_gt_u32_e64 s[10:11], v108, v173
	v_lshlrev_b32_e32 v105, 1, v104
	s_xor_b64 vcc, s[38:39], vcc
	s_xor_b64 s[6:7], s[38:39], s[6:7]
	s_xor_b64 s[8:9], s[38:39], s[8:9]
	s_xor_b64 s[10:11], s[38:39], s[10:11]
	v_add_u32_e32 v106, s57, v105
	v_cndmask_b32_e32 v100, 0, v100, vcc
	v_cndmask_b32_e64 v101, 0, v101, s[6:7]
	v_cndmask_b32_e64 v102, 0, v102, s[8:9]
	v_cndmask_b32_e64 v103, 0, v103, s[10:11]
	s_waitcnt lgkmcnt(0)
	v_mfma_f32_16x16x32_bf16 v[96:99], v[112:115], v[146:149], v[96:99]
	v_cvt_pk_bf16_f32 v100, v100, v101
	v_cvt_pk_bf16_f32 v101, v102, v103
	v_add_u32_e32 v175, v106, v174
	ds_write_b64 v175, v[100:101]
	v_or_b32_e32 v100, s12, v164
	v_cmp_gt_u32_e64 s[12:13], v104, v100
	v_cmp_ge_u32_e64 s[14:15], v104, v100
	v_cmp_gt_u32_e64 s[16:17], v107, v100
	v_cmp_gt_u32_e64 s[18:19], v108, v100
	s_xor_b64 s[12:13], s[38:39], s[12:13]
	s_xor_b64 s[14:15], s[38:39], s[14:15]
	s_xor_b64 s[16:17], s[38:39], s[16:17]
	s_xor_b64 s[18:19], s[38:39], s[18:19]
	v_cndmask_b32_e64 v96, 0, v96, s[12:13]
	v_cndmask_b32_e64 v97, 0, v97, s[14:15]
	v_cndmask_b32_e64 v98, 0, v98, s[16:17]
	v_cndmask_b32_e64 v99, 0, v99, s[18:19]
	v_mul_lo_u32 v176, v100, s3
	v_cvt_pk_bf16_f32 v96, v96, v97
	v_cvt_pk_bf16_f32 v97, v98, v99
	v_add_u32_e32 v177, v106, v176
	ds_write_b64 v177, v[96:97]
	v_mov_b64_e32 v[96:97], s[44:45]
	global_store_dwordx2 v[138:139], v[96:97], off
	global_store_dwordx2 v[138:139], v[96:97], off
	global_store_dwordx2 v[138:139], v[96:97], off
	global_store_dwordx2 v[138:139], v[96:97], off
	global_store_dwordx2 v[138:139], v[96:97], off
	s_lshl_b32 s31, s31, 5
	global_store_dwordx2 v[138:139], v[96:97], off
	v_lshl_or_b32 v96, s34, 4, v124
	s_add_u32 s20, s20, s31
	s_waitcnt lgkmcnt(0)
	v_lshl_add_u64 v[148:149], s[48:49], 0, v[142:143]
	v_lshlrev_b32_e32 v143, 2, v96
	v_lshlrev_b32_e32 v98, 1, v96
	s_addc_u32 s21, s21, 0
	v_lshlrev_b32_e32 v96, 1, v124
	v_mov_b32_e32 v97, v121
	v_lshl_add_u64 v[150:151], s[20:21], 0, v[96:97]
	v_mov_b32_e32 v100, 0
	v_mov_b32_e32 v96, 1.0
	v_lshl_add_u64 v[146:147], s[46:47], 0, v[120:121]
	s_mul_i32 s45, s66, 0x900
	s_mul_i32 s46, s68, 0x90
	v_add_u32_e32 v180, s58, v105
	s_mov_b32 s47, 62
	v_add_u32_e32 v182, v163, v98
	v_mov_b32_e32 v97, v96
	v_mov_b32_e32 v98, v96
	v_mov_b32_e32 v99, v96
	v_mov_b32_e32 v101, v100
	v_mov_b32_e32 v102, v100
	v_mov_b32_e32 v103, v100
	v_mov_b32_e32 v104, v100
	v_mov_b32_e32 v105, v100
	v_mov_b32_e32 v106, v100
	v_mov_b32_e32 v107, v100
	v_mov_b32_e32 v108, v100
	v_mov_b32_e32 v109, v100
	v_mov_b32_e32 v110, v100
	v_mov_b32_e32 v111, v100
	v_mov_b32_e32 v112, v100
	v_mov_b32_e32 v113, v100
	v_mov_b32_e32 v114, v100
	v_mov_b32_e32 v115, v100
	v_add_u32_e32 v206, s31, v161
	v_add_u32_e32 v207, s31, v162
	v_add_u32_e32 v208, s45, v156
	v_add_u32_e32 v209, s46, v156
	v_add_u32_e32 v210, s45, v159
	v_add_u32_e32 v211, s46, v159
	v_add_u32_e32 v212, v180, v174
	v_add_u32_e32 v213, v180, v176
	v_and_b32_e32 v240, 63, v158
	v_lshrrev_b32_e32 v241, 4, v240
	v_bfe_u32 v242, v240, 2, 2
	v_and_b32_e32 v243, 3, v240
	v_lshl_add_u32 v244, v241, 3, v242
	v_lshrrev_b32_e32 v245, 1, v242
	v_and_b32_e32 v246, 1, v241
	v_lshl_or_b32 v245, v246, 1, v245
	v_lshlrev_b32_e32 v244, 7, v244
	v_lshl_add_u32 v244, v243, 3, v244
	v_add_u32_e32 v244, 0x8800, v244
	v_xor_b32_e32 v246, 0, v245
	v_lshl_add_u32 v186, v246, 5, v244
	v_xor_b32_e32 v246, 1, v245
	v_lshl_add_u32 v187, v246, 5, v244
	v_xor_b32_e32 v246, 2, v245
	v_lshl_add_u32 v188, v246, 5, v244
	v_xor_b32_e32 v246, 3, v245
	v_lshl_add_u32 v189, v246, 5, v244
	s_lshr_b32 s77, s31, 5
	v_xor_b32_e32 v246, s77, v245
	v_lshl_add_u32 v206, v246, 5, v244
	v_readfirstlane_b32 s69, v158
	s_lshr_b32 s69, s69, 6

.Lev_skip_a:
	s_add_i32 s34, s49, 3
	v_sub_u32_e64 v32, 60, s44 clamp
	s_and_b64 s[20:21], exec, s[38:39]
	v_readfirstlane_b32 s20, v32
	s_cselect_b32 s66, s34, s20
	s_lshl_b32 s34, s66, 13
	s_lshl_b32 s67, s66, 14
	s_add_u32 s20, s43, s67
	s_addc_u32 s21, s63, 0
	v_lshl_add_u64 v[36:37], s[20:21], 0, v[120:121]
	global_load_dwordx4 v[32:35], v120, s[20:21] nt
	v_add_co_u32_e64 v36, s[20:21], s60, v36
	v_lshl_add_u64 v[48:49], v[146:147], 0, s[34:35]
	s_nop 0
	v_addc_co_u32_e64 v37, s[20:21], 0, v37, s[20:21]
	s_add_u32 s20, s64, s67
	s_addc_u32 s21, s65, 0
	v_lshl_add_u64 v[44:45], s[20:21], 0, v[120:121]
	global_load_dwordx4 v[36:39], v[36:37], off nt
	s_lshl_b32 s34, s66, 10
	global_load_dwordx4 v[40:43], v120, s[20:21] nt
	v_add_co_u32_e64 v44, s[20:21], s60, v44
	v_lshl_add_u64 v[52:53], v[148:149], 0, s[34:35]
	s_nop 0
	v_addc_co_u32_e64 v45, s[20:21], 0, v45, s[20:21]
	s_lshl_b32 s20, s49, 1
	s_add_i32 s34, s20, 4
	s_waitcnt vmcnt(15)
	v_mov_b32_e32 v214, v64
	v_mov_b32_e32 v215, v65
	v_mov_b32_e32 v216, v66
	v_mov_b32_e32 v217, v67
	v_lshl_add_u64 v[64:65], v[144:145], 0, s[34:35]
	s_add_i32 s34, 0, 0x1e400
	v_mov_b32_e32 v198, v56
	v_mov_b32_e32 v199, v57
	v_mov_b32_e32 v200, v58
	v_mov_b32_e32 v201, v59
	v_mov_b32_e32 v202, v60
	v_mov_b32_e32 v203, v61
	v_mov_b32_e32 v204, v62
	v_mov_b32_e32 v205, v63
	s_waitcnt vmcnt(14)
	v_mov_b32_e32 v242, v68
	v_mov_b32_e32 v243, v69
	v_mov_b32_e32 v244, v70
	v_mov_b32_e32 v245, v71
	v_add_u32_e32 v116, s34, v143
	ds_read_b128 v[190:193], v116
	v_and_b32_e32 v66, 0xfff, v64
	v_cmp_ne_u32_e64 s[20:21], 0, v66
	v_add_u32_e32 v185, 0, v143
	v_add_u32_e32 v116, 0x1e600, v185
	s_waitcnt lgkmcnt(0)
	v_pk_mul_f32 v[192:193], v[98:99], v[192:193]
	v_pk_mul_f32 v[190:191], v[96:97], v[190:191]
	v_pk_mul_f32 v[98:99], v[102:103], v[192:193]
	v_pk_mul_f32 v[96:97], v[100:101], v[190:191]
	v_cndmask_b32_e64 v56, 0, 1, s[20:21]
	v_cvt_pk_bf16_f32 v100, v96, v97
	v_cvt_pk_bf16_f32 v101, v98, v99
	v_sub_co_u32_e64 v56, s[20:21], v64, v56
	ds_read_b128 v[116:119], v116
	ds_write_b64 v182, v[100:101]
	v_pk_mul_f32 v[100:101], v[104:105], v[190:191]
	v_pk_mul_f32 v[102:103], v[106:107], v[192:193]
	v_subbrev_co_u32_e64 v57, s[20:21], 0, v65, s[20:21]
	v_cvt_pk_bf16_f32 v104, v100, v101
	v_cvt_pk_bf16_f32 v105, v102, v103
	v_cmp_ne_u32_e64 s[20:21], s62, v66
	ds_write_b64 v182, v[104:105] offset:4352
	v_pk_mul_f32 v[104:105], v[108:109], v[190:191]
	v_pk_mul_f32 v[106:107], v[110:111], v[192:193]
	v_cndmask_b32_e64 v66, 0, 1, s[20:21]
	v_mov_b32_e32 v67, s35
	v_cvt_pk_bf16_f32 v108, v104, v105
	v_cvt_pk_bf16_f32 v109, v106, v107
	v_lshlrev_b64 v[68:69], 11, v[64:65]
	v_lshl_add_u64 v[64:65], v[64:65], 0, v[66:67]
	ds_write_b64 v182, v[108:109] offset:8704
	v_pk_mul_f32 v[108:109], v[112:113], v[190:191]
	v_pk_mul_f32 v[110:111], v[114:115], v[192:193]
	v_lshlrev_b64 v[56:57], 11, v[56:57]
	v_lshlrev_b64 v[64:65], 11, v[64:65]
	v_cvt_pk_bf16_f32 v112, v108, v109
	v_cvt_pk_bf16_f32 v113, v110, v111
	v_lshl_add_u64 v[56:57], v[134:135], 0, v[56:57]
	v_lshl_add_u64 v[60:61], v[134:135], 0, v[68:69]
	v_lshl_add_u64 v[64:65], v[134:135], 0, v[64:65]
	v_lshl_add_u64 v[68:69], v[136:137], 0, v[68:69]
	ds_write_b64 v182, v[112:113] offset:13056
	global_load_dwordx4 v[44:47], v[44:45], off nt
	global_load_dwordx4 v[48:51], v[48:49], off nt
	global_load_dwordx4 v[52:55], v[52:53], off
	global_load_dwordx4 v[56:59], v[56:57], off
	s_lshl_b32 s48, s48, 6
	global_load_dwordx4 v[60:63], v[60:61], off
	s_nop 0
	global_load_dwordx4 v[64:67], v[64:65], off
	s_nop 0
	global_load_dwordx4 v[68:71], v[68:69], off nt
	s_waitcnt lgkmcnt(0)
	s_barrier
	ds_read_b128 v[218:221], v170 offset:61440
	ds_read_b128 v[222:225], v171 offset:44032
	ds_read_b128 v[226:229], v172 offset:44032
	ds_read_b128 v[230:233], v170 offset:61504
	ds_read_b128 v[234:237], v171 offset:44096
	ds_read_b128 v[238:241], v172 offset:44096
	v_and_b32_e32 v250, 0xfff, v184
	v_cmp_ne_u32_e64 s[20:21], 0, v250
	v_add_u32_e32 v184, 4, v184
	s_nop 0
	v_cndmask_b32_e64 v198, 0, v198, s[20:21]
	v_cndmask_b32_e64 v199, 0, v199, s[20:21]
	v_cndmask_b32_e64 v200, 0, v200, s[20:21]
	v_cndmask_b32_e64 v201, 0, v201, s[20:21]
	v_cmp_ne_u32_e64 s[20:21], s62, v250
	v_lshlrev_b32_e32 v246, 16, v202
	v_and_b32_e32 v247, 0xffff0000, v202
	v_cndmask_b32_e64 v214, 0, v214, s[20:21]
	v_cndmask_b32_e64 v215, 0, v215, s[20:21]
	v_cndmask_b32_e64 v216, 0, v216, s[20:21]
	v_cndmask_b32_e64 v217, 0, v217, s[20:21]
	v_pk_mul_f32 v[246:247], v[8:9], v[246:247]
	v_lshlrev_b32_e32 v248, 16, v198
	v_and_b32_e32 v249, 0xffff0000, v198
	v_pk_fma_f32 v[246:247], v[0:1], v[248:249], v[246:247]
	v_lshlrev_b32_e32 v248, 16, v214
	v_and_b32_e32 v249, 0xffff0000, v214
	v_pk_fma_f32 v[246:247], v[16:17], v[248:249], v[246:247]
	v_pk_add_f32 v[246:247], v[24:25], v[246:247]
	v_lshlrev_b32_e32 v248, 16, v242
	v_and_b32_e32 v249, 0xffff0000, v242
	v_pk_mul_f32 v[246:247], v[246:247], v[248:249]
	v_cvt_pk_bf16_f32 v198, v246, v247
	v_lshlrev_b32_e32 v246, 16, v203
	v_and_b32_e32 v247, 0xffff0000, v203
	v_pk_mul_f32 v[246:247], v[10:11], v[246:247]
	v_lshlrev_b32_e32 v248, 16, v199
	v_and_b32_e32 v249, 0xffff0000, v199
	v_pk_fma_f32 v[246:247], v[2:3], v[248:249], v[246:247]
	v_lshlrev_b32_e32 v248, 16, v215
	v_and_b32_e32 v249, 0xffff0000, v215
	v_pk_fma_f32 v[246:247], v[18:19], v[248:249], v[246:247]
	v_pk_add_f32 v[246:247], v[26:27], v[246:247]
	v_lshlrev_b32_e32 v248, 16, v243
	v_and_b32_e32 v249, 0xffff0000, v243
	v_pk_mul_f32 v[246:247], v[246:247], v[248:249]
	v_cvt_pk_bf16_f32 v199, v246, v247
	v_lshlrev_b32_e32 v246, 16, v204
	v_and_b32_e32 v247, 0xffff0000, v204
	v_pk_mul_f32 v[246:247], v[12:13], v[246:247]
	v_lshlrev_b32_e32 v248, 16, v200
	v_and_b32_e32 v249, 0xffff0000, v200
	v_pk_fma_f32 v[246:247], v[4:5], v[248:249], v[246:247]
	v_lshlrev_b32_e32 v248, 16, v216
	v_and_b32_e32 v249, 0xffff0000, v216
	v_pk_fma_f32 v[246:247], v[20:21], v[248:249], v[246:247]
	v_pk_add_f32 v[246:247], v[28:29], v[246:247]
	v_lshlrev_b32_e32 v248, 16, v244
	v_and_b32_e32 v249, 0xffff0000, v244
	v_pk_mul_f32 v[246:247], v[246:247], v[248:249]
	v_cvt_pk_bf16_f32 v200, v246, v247
	v_lshlrev_b32_e32 v246, 16, v205
	v_and_b32_e32 v247, 0xffff0000, v205
	v_pk_mul_f32 v[246:247], v[14:15], v[246:247]
	v_lshlrev_b32_e32 v248, 16, v201
	v_and_b32_e32 v249, 0xffff0000, v201
	v_pk_fma_f32 v[246:247], v[6:7], v[248:249], v[246:247]
	v_lshlrev_b32_e32 v248, 16, v217
	v_and_b32_e32 v249, 0xffff0000, v217
	v_pk_fma_f32 v[246:247], v[22:23], v[248:249], v[246:247]
	v_pk_add_f32 v[246:247], v[30:31], v[246:247]
	v_lshlrev_b32_e32 v248, 16, v245
	v_and_b32_e32 v249, 0xffff0000, v245
	v_pk_mul_f32 v[246:247], v[246:247], v[248:249]
	v_cvt_pk_bf16_f32 v201, v246, v247
	global_store_dwordx4 v[152:153], v[198:201], off
	ds_read_b128 v[242:245], v170 offset:61568
	ds_read_b128 v[246:249], v171 offset:44160
	ds_read_b128 v[250:253], v172 offset:44160
	s_waitcnt lgkmcnt(6)
	v_mfma_f32_16x16x32_bf16 v[190:193], v[218:221], v[222:225], 0
	v_mfma_f32_16x16x32_bf16 v[194:197], v[218:221], v[226:229], 0
	ds_read_b128 v[218:221], v170 offset:61632
	ds_read_b128 v[222:225], v171 offset:44224
	ds_read_b128 v[226:229], v172 offset:44224
	s_waitcnt lgkmcnt(6)
	v_mfma_f32_16x16x32_bf16 v[190:193], v[230:233], v[234:237], v[190:193]
	v_mfma_f32_16x16x32_bf16 v[194:197], v[230:233], v[238:241], v[194:197]
	ds_read_b64_tr_b16 v[230:231], v206
	ds_read_b64_tr_b16 v[232:233], v206 offset:512
	ds_read_b128 v[234:237], v208
	ds_read_b128 v[238:241], v209
	s_waitcnt lgkmcnt(7)
	v_mfma_f32_16x16x32_bf16 v[190:193], v[242:245], v[246:249], v[190:193]
	v_mfma_f32_16x16x32_bf16 v[194:197], v[242:245], v[250:253], v[194:197]
	ds_read_b64_tr_b16 v[242:243], v206 offset:4096
	ds_read_b64_tr_b16 v[244:245], v206 offset:4608
	ds_read_b128 v[246:249], v208 offset:64
	ds_read_b128 v[250:253], v209 offset:64
	s_waitcnt lgkmcnt(8)
	v_mfma_f32_16x16x32_bf16 v[190:193], v[218:221], v[222:225], v[190:193]
	v_mfma_f32_16x16x32_bf16 v[194:197], v[218:221], v[226:229], v[194:197]
	ds_read_b128 v[218:221], v183
	ds_read_b128 v[222:225], v171
	ds_read_b128 v[226:229], v172
	s_waitcnt lgkmcnt(7)
	v_mfma_f32_16x16x32_bf16 v[198:201], v[230:233], v[234:237], 0
	v_mfma_f32_16x16x32_bf16 v[202:205], v[230:233], v[238:241], 0
	ds_read_b128 v[230:233], v183 offset:64
	ds_read_b128 v[234:237], v171 offset:64
	ds_read_b128 v[238:241], v172 offset:64
	s_waitcnt lgkmcnt(6)
	v_mfma_f32_16x16x32_bf16 v[198:201], v[242:245], v[246:249], v[198:201]
	v_mfma_f32_16x16x32_bf16 v[202:205], v[242:245], v[250:253], v[202:205]
	ds_read_b128 v[242:245], v183 offset:128
	ds_read_b128 v[246:249], v171 offset:128
	ds_read_b128 v[250:253], v172 offset:128
	v_cndmask_b32_e32 v190, 0, v190, vcc
	v_cndmask_b32_e64 v191, 0, v191, s[6:7]
	v_cndmask_b32_e64 v192, 0, v192, s[8:9]
	v_cndmask_b32_e64 v193, 0, v193, s[10:11]
	v_cvt_pk_bf16_f32 v190, v190, v191
	v_cvt_pk_bf16_f32 v191, v192, v193
	v_cndmask_b32_e64 v194, 0, v194, s[12:13]
	v_cndmask_b32_e64 v195, 0, v195, s[14:15]
	v_cndmask_b32_e64 v196, 0, v196, s[16:17]
	v_cndmask_b32_e64 v197, 0, v197, s[18:19]
	v_cvt_pk_bf16_f32 v194, v194, v195
	v_cvt_pk_bf16_f32 v195, v196, v197
	ds_write_b64 v212, v[190:191]
	ds_write_b64 v213, v[194:195]
	s_waitcnt lgkmcnt(8)
	v_mfma_f32_16x16x32_bf16 v[198:201], v[218:221], v[222:225], v[198:201]
	v_mfma_f32_16x16x32_bf16 v[202:205], v[218:221], v[226:229], v[202:205]
	ds_read_b64_tr_b16 v[190:191], v178 offset:17408
	ds_read_b64_tr_b16 v[192:193], v178 offset:18496
	ds_read_b64_tr_b16 v[194:195], v178 offset:26112
	ds_read_b64_tr_b16 v[196:197], v178 offset:27200
	s_waitcnt lgkmcnt(9)
	v_mfma_f32_16x16x32_bf16 v[198:201], v[230:233], v[234:237], v[198:201]
	v_mfma_f32_16x16x32_bf16 v[202:205], v[230:233], v[238:241], v[202:205]
	ds_read_b128 v[230:233], v183 offset:192
	ds_read_b128 v[234:237], v171 offset:192
	ds_read_b128 v[238:241], v172 offset:192
	s_waitcnt lgkmcnt(9)
	v_mfma_f32_16x16x32_bf16 v[198:201], v[242:245], v[246:249], v[198:201]
	v_mfma_f32_16x16x32_bf16 v[202:205], v[242:245], v[250:253], v[202:205]
	ds_read_b64_tr_b16 v[242:243], v186
	ds_read_b64_tr_b16 v[244:245], v186 offset:512
	ds_read_b64_tr_b16 v[246:247], v187
	ds_read_b64_tr_b16 v[248:249], v187 offset:512
	s_waitcnt lgkmcnt(7)
	ds_read_b64_tr_b16 v[218:219], v188
	ds_read_b64_tr_b16 v[220:221], v188 offset:512
	ds_read_b64_tr_b16 v[222:223], v189
	ds_read_b64_tr_b16 v[224:225], v189 offset:512
	s_waitcnt lgkmcnt(8)
	v_mfma_f32_16x16x32_bf16 v[198:201], v[230:233], v[234:237], v[198:201]
	v_mfma_f32_16x16x32_bf16 v[202:205], v[230:233], v[238:241], v[202:205]
	ds_read_b64_tr_b16 v[230:231], v186 offset:4096
	ds_read_b64_tr_b16 v[232:233], v186 offset:4608
	ds_read_b64_tr_b16 v[234:235], v187 offset:4096
	ds_read_b64_tr_b16 v[236:237], v187 offset:4608
	s_waitcnt lgkmcnt(8)
	v_mfma_f32_16x16x32_bf16 v[96:99], v[190:193], v[242:245], v[96:99]
	v_mfma_f32_16x16x32_bf16 v[100:103], v[190:193], v[246:249], v[100:103]
	ds_read_b64_tr_b16 v[242:243], v188 offset:4096
	ds_read_b64_tr_b16 v[244:245], v188 offset:4608
	ds_read_b64_tr_b16 v[246:247], v189 offset:4096
	ds_read_b64_tr_b16 v[248:249], v189 offset:4608
	v_cvt_pk_bf16_f32 v198, v198, v199
	v_cvt_pk_bf16_f32 v199, v200, v201
	v_add_u32_e32 v254, s48, v173
	v_mad_u64_u32 v[254:255], s[20:21], v254, s42, 0
	v_lshl_add_u64 v[254:255], v[254:255], 1, v[150:151]
	v_cvt_pk_bf16_f32 v202, v202, v203
	v_cvt_pk_bf16_f32 v203, v204, v205
	global_store_dwordx2 v[254:255], v[198:199], off
	v_add_u32_e32 v254, s48, v179
	v_mad_u64_u32 v[254:255], s[20:21], v254, s42, 0
	v_lshl_add_u64 v[254:255], v[254:255], 1, v[150:151]
	global_store_dwordx2 v[254:255], v[202:203], off
	s_waitcnt lgkmcnt(8)
	v_mfma_f32_16x16x32_bf16 v[104:107], v[190:193], v[218:221], v[104:107]
	v_mfma_f32_16x16x32_bf16 v[214:217], v[190:193], v[222:225], v[108:111]
	s_waitcnt lgkmcnt(4)
	v_mfma_f32_16x16x32_bf16 v[112:115], v[194:197], v[230:233], v[96:99]
	v_mfma_f32_16x16x32_bf16 v[108:111], v[194:197], v[234:237], v[100:103]
	s_waitcnt lgkmcnt(0)
	v_mfma_f32_16x16x32_bf16 v[104:107], v[194:197], v[242:245], v[104:107]
	v_mfma_f32_16x16x32_bf16 v[100:103], v[194:197], v[246:249], v[214:217]
	s_min_u32 s20, s44, 59
	s_waitcnt lgkmcnt(0)
	s_barrier
	s_waitcnt vmcnt(20)
	ds_write_b128 v168, v[72:75]
	s_waitcnt vmcnt(19)
	ds_write_b128 v168, v[80:83] offset:8704
	s_waitcnt vmcnt(18)
	ds_write_b128 v168, v[76:79] offset:17408
	s_waitcnt vmcnt(17)
	ds_write_b128 v168, v[84:87] offset:26112
	s_waitcnt vmcnt(16)
	ds_write_b128 v169, v[88:91] offset:34816
	v_add_u32_e32 v72, s34, v154
	s_add_i32 s34, s20, 4
	s_waitcnt vmcnt(15)
	s_cmp_lg_u32 s69, 0
	s_cbranch_scc1 .Lev_skip_b
	ds_write_b128 v72, v[92:95]
.Lev_skip_b:
	v_sub_u32_e64 v72, 59, s44 clamp
	s_and_b64 s[20:21], exec, s[38:39]
	v_readfirstlane_b32 s20, v72
	s_cselect_b32 s48, s34, s20
	v_add_u32_e32 v96, s61, v143
	s_lshl_b32 s34, s48, 13
	s_lshl_b32 s49, s48, 14
	ds_read_b128 v[222:225], v96
	s_add_u32 s20, s43, s49
	s_addc_u32 s21, s63, 0
	v_lshl_add_u64 v[76:77], s[20:21], 0, v[120:121]
	global_load_dwordx4 v[72:75], v120, s[20:21] nt
	v_add_co_u32_e64 v76, s[20:21], s60, v76
	s_waitcnt lgkmcnt(0)
	v_pk_mul_f32 v[118:119], v[118:119], v[224:225]
	v_addc_co_u32_e64 v77, s[20:21], 0, v77, s[20:21]
	v_pk_mul_f32 v[116:117], v[116:117], v[222:223]
	s_add_u32 s20, s64, s49
	v_pk_mul_f32 v[114:115], v[114:115], v[118:119]
	v_pk_mul_f32 v[112:113], v[112:113], v[116:117]
	s_addc_u32 s21, s65, 0
	v_add_u32_e32 v96, 0x1ea00, v185
	v_cvt_pk_bf16_f32 v222, v112, v113
	v_cvt_pk_bf16_f32 v223, v114, v115
	v_pk_mul_f32 v[110:111], v[110:111], v[118:119]
	v_pk_mul_f32 v[108:109], v[108:109], v[116:117]
	v_lshl_add_u64 v[84:85], s[20:21], 0, v[120:121]
	ds_read_b128 v[96:99], v96
	ds_write_b64 v182, v[222:223]
	v_cvt_pk_bf16_f32 v222, v108, v109
	v_cvt_pk_bf16_f32 v223, v110, v111
	v_pk_mul_f32 v[106:107], v[106:107], v[118:119]
	v_pk_mul_f32 v[104:105], v[104:105], v[116:117]
	v_pk_mul_f32 v[102:103], v[102:103], v[118:119]
	v_pk_mul_f32 v[100:101], v[100:101], v[116:117]
	global_load_dwordx4 v[80:83], v[76:77], off nt
	v_lshl_add_u64 v[88:89], v[146:147], 0, s[34:35]
	global_load_dwordx4 v[76:79], v120, s[20:21] nt
	v_add_co_u32_e64 v84, s[20:21], s60, v84
	s_lshl_b32 s34, s48, 10
	ds_write_b64 v182, v[222:223] offset:4352
	v_cvt_pk_bf16_f32 v222, v104, v105
	v_cvt_pk_bf16_f32 v223, v106, v107
	v_cvt_pk_bf16_f32 v116, v100, v101
	v_cvt_pk_bf16_f32 v117, v102, v103
	v_addc_co_u32_e64 v85, s[20:21], 0, v85, s[20:21]
	v_lshl_add_u64 v[92:93], v[148:149], 0, s[34:35]
	ds_write_b64 v182, v[222:223] offset:8704
	ds_write_b64 v182, v[116:117] offset:13056
	global_load_dwordx4 v[84:87], v[84:85], off nt
	v_add_u32_e32 v185, s31, v162
	global_load_dwordx4 v[88:91], v[88:89], off nt
	v_add_u32_e32 v194, s45, v159
	global_load_dwordx4 v[92:95], v[92:93], off
	s_waitcnt lgkmcnt(0)
	s_barrier
	ds_read_b128 v[218:221], v170 offset:17408
	ds_read_b128 v[222:225], v171
	ds_read_b128 v[226:229], v172
	ds_read_b128 v[230:233], v170 offset:17472
	ds_read_b128 v[234:237], v171 offset:64
	ds_read_b128 v[238:241], v172 offset:64
	ds_read_b128 v[242:245], v170 offset:17536
	ds_read_b128 v[246:249], v171 offset:128
	ds_read_b128 v[250:253], v172 offset:128
	s_add_i32 s34, s44, 1
	s_and_b64 s[20:21], exec, s[38:39]
	s_cselect_b32 s20, s34, s47
	s_lshl_b32 s34, s20, 6
	s_add_i32 s47, s47, -2
	v_lshl_add_u64 v[152:153], v[152:153], 0, s[36:37]
	s_waitcnt lgkmcnt(6)
	v_mfma_f32_16x16x32_bf16 v[190:193], v[218:221], v[222:225], 0
	v_mfma_f32_16x16x32_bf16 v[194:197], v[218:221], v[226:229], 0
	ds_read_b128 v[218:221], v170 offset:17600
	ds_read_b128 v[222:225], v171 offset:192
	ds_read_b128 v[226:229], v172 offset:192
	s_waitcnt lgkmcnt(6)
	v_mfma_f32_16x16x32_bf16 v[190:193], v[230:233], v[234:237], v[190:193]
	v_mfma_f32_16x16x32_bf16 v[194:197], v[230:233], v[238:241], v[194:197]
	ds_read_b64_tr_b16 v[230:231], v206 offset:44032
	ds_read_b64_tr_b16 v[232:233], v206 offset:44544
	ds_read_b128 v[234:237], v210
	ds_read_b128 v[238:241], v211
	s_waitcnt lgkmcnt(7)
	v_mfma_f32_16x16x32_bf16 v[190:193], v[242:245], v[246:249], v[190:193]
	v_mfma_f32_16x16x32_bf16 v[194:197], v[242:245], v[250:253], v[194:197]
	ds_read_b64_tr_b16 v[242:243], v206 offset:48128
	ds_read_b64_tr_b16 v[244:245], v206 offset:48640
	ds_read_b128 v[246:249], v210 offset:64
	ds_read_b128 v[250:253], v211 offset:64
	s_waitcnt lgkmcnt(8)
	v_mfma_f32_16x16x32_bf16 v[190:193], v[218:221], v[222:225], v[190:193]
	v_mfma_f32_16x16x32_bf16 v[194:197], v[218:221], v[226:229], v[194:197]
	ds_read_b128 v[218:221], v183
	ds_read_b128 v[222:225], v171 offset:44032
	ds_read_b128 v[226:229], v172 offset:44032
	s_waitcnt lgkmcnt(7)
	v_mfma_f32_16x16x32_bf16 v[198:201], v[230:233], v[234:237], 0
	v_mfma_f32_16x16x32_bf16 v[202:205], v[230:233], v[238:241], 0
	ds_read_b128 v[230:233], v183 offset:64
	ds_read_b128 v[234:237], v171 offset:44096
	ds_read_b128 v[238:241], v172 offset:44096
	s_waitcnt lgkmcnt(6)
	v_mfma_f32_16x16x32_bf16 v[198:201], v[242:245], v[246:249], v[198:201]
	v_mfma_f32_16x16x32_bf16 v[202:205], v[242:245], v[250:253], v[202:205]
	ds_read_b128 v[242:245], v183 offset:128
	ds_read_b128 v[246:249], v171 offset:44160
	ds_read_b128 v[250:253], v172 offset:44160
	v_cndmask_b32_e32 v190, 0, v190, vcc
	v_cndmask_b32_e64 v191, 0, v191, s[6:7]
	v_cndmask_b32_e64 v192, 0, v192, s[8:9]
	v_cndmask_b32_e64 v193, 0, v193, s[10:11]
	v_cvt_pk_bf16_f32 v190, v190, v191
	v_cvt_pk_bf16_f32 v191, v192, v193
	v_cndmask_b32_e64 v194, 0, v194, s[12:13]
	v_cndmask_b32_e64 v195, 0, v195, s[14:15]
	v_cndmask_b32_e64 v196, 0, v196, s[16:17]
	v_cndmask_b32_e64 v197, 0, v197, s[18:19]
	v_cvt_pk_bf16_f32 v194, v194, v195
	v_cvt_pk_bf16_f32 v195, v196, v197
	ds_write_b64 v175, v[190:191]
	ds_write_b64 v177, v[194:195]
	s_waitcnt lgkmcnt(8)
	v_mfma_f32_16x16x32_bf16 v[198:201], v[218:221], v[222:225], v[198:201]
	v_mfma_f32_16x16x32_bf16 v[202:205], v[218:221], v[226:229], v[202:205]
	ds_read_b64_tr_b16 v[190:191], v178 offset:61440
	ds_read_b64_tr_b16 v[192:193], v178 offset:62528
	ds_read_b64_tr_b16 v[194:195], v181 offset:8704
	ds_read_b64_tr_b16 v[196:197], v181 offset:9792
	s_waitcnt lgkmcnt(9)
	v_mfma_f32_16x16x32_bf16 v[198:201], v[230:233], v[234:237], v[198:201]
	v_mfma_f32_16x16x32_bf16 v[202:205], v[230:233], v[238:241], v[202:205]
	ds_read_b128 v[230:233], v183 offset:192
	ds_read_b128 v[234:237], v171 offset:44224
	ds_read_b128 v[238:241], v172 offset:44224
	s_waitcnt lgkmcnt(9)
	v_mfma_f32_16x16x32_bf16 v[198:201], v[242:245], v[246:249], v[198:201]
	v_mfma_f32_16x16x32_bf16 v[202:205], v[242:245], v[250:253], v[202:205]
	ds_read_b64_tr_b16 v[242:243], v186 offset:44032
	ds_read_b64_tr_b16 v[244:245], v186 offset:44544
	ds_read_b64_tr_b16 v[246:247], v187 offset:44032
	ds_read_b64_tr_b16 v[248:249], v187 offset:44544
	s_waitcnt lgkmcnt(7)
	ds_read_b64_tr_b16 v[218:219], v188 offset:44032
	ds_read_b64_tr_b16 v[220:221], v188 offset:44544
	ds_read_b64_tr_b16 v[222:223], v189 offset:44032
	ds_read_b64_tr_b16 v[224:225], v189 offset:44544
	s_waitcnt lgkmcnt(8)
	v_mfma_f32_16x16x32_bf16 v[198:201], v[230:233], v[234:237], v[198:201]
	v_mfma_f32_16x16x32_bf16 v[202:205], v[230:233], v[238:241], v[202:205]
	ds_read_b64_tr_b16 v[230:231], v186 offset:48128
	ds_read_b64_tr_b16 v[232:233], v186 offset:48640
	ds_read_b64_tr_b16 v[234:235], v187 offset:48128
	ds_read_b64_tr_b16 v[236:237], v187 offset:48640
	s_waitcnt lgkmcnt(8)
	v_mfma_f32_16x16x32_bf16 v[112:115], v[190:193], v[242:245], v[112:115]
	v_mfma_f32_16x16x32_bf16 v[108:111], v[190:193], v[246:249], v[108:111]
	ds_read_b64_tr_b16 v[242:243], v188 offset:48128
	ds_read_b64_tr_b16 v[244:245], v188 offset:48640
	ds_read_b64_tr_b16 v[246:247], v189 offset:48128
	ds_read_b64_tr_b16 v[248:249], v189 offset:48640
	v_cvt_pk_bf16_f32 v198, v198, v199
	v_cvt_pk_bf16_f32 v199, v200, v201
	v_add_u32_e32 v254, s34, v173
	v_mad_u64_u32 v[254:255], s[20:21], v254, s42, 0
	v_lshl_add_u64 v[254:255], v[254:255], 1, v[150:151]
	v_cvt_pk_bf16_f32 v202, v202, v203
	v_cvt_pk_bf16_f32 v203, v204, v205
	global_store_dwordx2 v[254:255], v[198:199], off
	v_add_u32_e32 v254, s34, v179
	v_mad_u64_u32 v[254:255], s[20:21], v254, s42, 0
	v_lshl_add_u64 v[254:255], v[254:255], 1, v[150:151]
	global_store_dwordx2 v[254:255], v[202:203], off
	s_waitcnt lgkmcnt(8)
	v_mfma_f32_16x16x32_bf16 v[214:217], v[190:193], v[218:221], v[104:107]
	v_mfma_f32_16x16x32_bf16 v[116:119], v[190:193], v[222:225], v[100:103]
	s_waitcnt lgkmcnt(4)
	v_mfma_f32_16x16x32_bf16 v[100:103], v[194:197], v[230:233], v[112:115]
	v_mfma_f32_16x16x32_bf16 v[104:107], v[194:197], v[234:237], v[108:111]
	s_waitcnt lgkmcnt(0)
	v_mfma_f32_16x16x32_bf16 v[108:111], v[194:197], v[242:245], v[214:217]
	v_mfma_f32_16x16x32_bf16 v[112:115], v[194:197], v[246:249], v[116:119]
	s_add_i32 s20, s44, 2
	s_cmp_lt_u32 s44, 62
	s_mov_b32 s44, s20
	s_waitcnt lgkmcnt(0)
	s_barrier
	s_cbranch_scc1 .LBB0_350
	s_add_i32 s30, s30, s28
	v_lshl_add_u64 v[140:141], v[140:141], 0, s[26:27]
	s_cmpk_lt_i32 s30, 0x100
	v_add_u32_e32 v165, s29, v165
	s_cbranch_scc1 .LBB0_344
